# FU epilogue ACT stores write-through (sc1) on top of ladder + combo: nothing of ACT left dirty in L2 for the barrier write-back
# speedup vs baseline: 1.0051x; 1.0051x over previous
; __device__ __forceinline__ u32x4 pack8(f32x4 v0, f32x4 v1) { u32x4 w; w.x = cvt_pk_bf16(v0[0], v0[1]); w.y = cvt_pk_bf16(v0[2], v0[3]); w.z = cvt_pk_bf16(v1[0], v1[1]); w.w = cvt_pk_bf16(v1[2], v1[3]); return w; }
;     __device__ __forceinline__ void operator()(const f32x4 (&acc)[2][2][4][2], const Unit& u, int wr, int wc, int fr, int fq) const {
;         const int row0 = u.pm * BM + wr * 64 + fr, col0 = u.pn * HALF + wc * 32 + 8 * fq;
;         bf16_t* const p0 = ACT + (size_t)row0 * 5632 + col0;
; #pragma unroll
;         for (int ai = 0; ai < 2; ++ai)
; #pragma unroll
;             for (int m = 0; m < 4; ++m) {
;                 const f32x4 g0 = acc[ai][0][m][0], g1 = acc[ai][0][m][1];
;                 const f32x4 v0 = g0 * sigmoid4(g0) * acc[ai][1][m][0], v1 = g1 * sigmoid4(g1) * acc[ai][1][m][1];
;                 store16_wt(p0 + (size_t)(ai * HALF + m * 16) * 5632, pack8(v0, v1)); }
;     }
.LBB0_1461:
	v_lshl_add_u32 v145, s70, 8, v1
	v_lshl_or_b32 v144, s69, 7, v148
	v_mov_b64_e32 v[146:147], s[8:9]
	s_movk_i32 s0, 0x2c00
	v_mad_i64_i32 v[146:147], s[0:1], v145, s0, v[146:147]
	v_ashrrev_i32_e32 v145, 31, v144
	v_lshl_add_u64 v[144:145], v[144:145], 1, v[146:147]
	v_pk_mul_f32 v[146:147], v[128:129], s[74:75] op_sel_hi:[1,0]
	v_pk_mul_f32 v[150:151], v[130:131], s[74:75] op_sel_hi:[1,0]
	v_exp_f32_e32 v146, v146
	v_exp_f32_e32 v147, v147
	v_exp_f32_e32 v150, v150
	v_exp_f32_e32 v151, v151
	s_mov_b32 s0, 0x160000
	v_pk_add_f32 v[146:147], v[146:147], 1.0 op_sel_hi:[1,0]
	s_mov_b64 s[34:35], -1
	v_pk_add_f32 v[150:151], v[150:151], 1.0 op_sel_hi:[1,0]
	v_rcp_f32_e32 v146, v146
	v_rcp_f32_e32 v147, v147
	v_rcp_f32_e32 v150, v150
	v_rcp_f32_e32 v151, v151
	v_pk_mul_f32 v[128:129], v[128:129], v[146:147]
	s_nop 0
	v_pk_mul_f32 v[124:125], v[124:125], v[128:129]
	v_pk_mul_f32 v[130:131], v[130:131], v[150:151]
	v_pk_mul_f32 v[128:129], v[120:121], s[74:75] op_sel_hi:[1,0]
	v_pk_mul_f32 v[126:127], v[126:127], v[130:131]
	v_pk_mul_f32 v[130:131], v[122:123], s[74:75] op_sel_hi:[1,0]
	v_exp_f32_e32 v128, v128
	v_exp_f32_e32 v129, v129
	v_exp_f32_e32 v130, v130
	v_exp_f32_e32 v131, v131
	v_pk_add_f32 v[128:129], v[128:129], 1.0 op_sel_hi:[1,0]
	s_nop 0
	v_rcp_f32_e32 v128, v128
	v_pk_add_f32 v[130:131], v[130:131], 1.0 op_sel_hi:[1,0]
	v_rcp_f32_e32 v129, v129
	v_rcp_f32_e32 v130, v130
	v_rcp_f32_e32 v131, v131
	v_pk_mul_f32 v[120:121], v[120:121], v[128:129]
	v_pk_mul_f32 v[122:123], v[122:123], v[130:131]
	s_nop 0
	v_pk_mul_f32 v[122:123], v[118:119], v[122:123]
	v_pk_mul_f32 v[118:119], v[116:117], v[120:121]
	v_cvt_pk_bf16_f32 v116, v124, v125
	v_cvt_pk_bf16_f32 v117, v126, v127
	v_cvt_pk_bf16_f32 v118, v118, v119
	v_cvt_pk_bf16_f32 v119, v122, v123
	global_store_dwordx4 v[144:145], v[116:119], off sc1
	s_nop 1
	v_pk_mul_f32 v[116:117], v[112:113], s[74:75] op_sel_hi:[1,0]
	v_pk_mul_f32 v[118:119], v[114:115], s[74:75] op_sel_hi:[1,0]
	v_exp_f32_e32 v116, v116
	v_exp_f32_e32 v117, v117
	v_exp_f32_e32 v118, v118
	v_exp_f32_e32 v119, v119
	v_pk_add_f32 v[116:117], v[116:117], 1.0 op_sel_hi:[1,0]
	s_nop 0
	v_rcp_f32_e32 v116, v116
	v_pk_add_f32 v[118:119], v[118:119], 1.0 op_sel_hi:[1,0]
	v_rcp_f32_e32 v117, v117
	v_rcp_f32_e32 v118, v118
	v_rcp_f32_e32 v119, v119
	v_pk_mul_f32 v[112:113], v[112:113], v[116:117]
	s_nop 0
	v_pk_mul_f32 v[108:109], v[108:109], v[112:113]
	v_pk_mul_f32 v[114:115], v[114:115], v[118:119]
	v_pk_mul_f32 v[112:113], v[104:105], s[74:75] op_sel_hi:[1,0]
	v_pk_mul_f32 v[110:111], v[110:111], v[114:115]
	v_pk_mul_f32 v[114:115], v[106:107], s[74:75] op_sel_hi:[1,0]
	v_exp_f32_e32 v112, v112
	v_exp_f32_e32 v113, v113
	v_exp_f32_e32 v114, v114
	v_exp_f32_e32 v115, v115
	v_pk_add_f32 v[112:113], v[112:113], 1.0 op_sel_hi:[1,0]
	s_nop 0
	v_rcp_f32_e32 v112, v112
	v_pk_add_f32 v[114:115], v[114:115], 1.0 op_sel_hi:[1,0]
	v_rcp_f32_e32 v113, v113
	v_rcp_f32_e32 v114, v114
	v_rcp_f32_e32 v115, v115
	v_pk_mul_f32 v[104:105], v[104:105], v[112:113]
	v_pk_mul_f32 v[106:107], v[106:107], v[114:115]
	s_nop 0
	v_pk_mul_f32 v[106:107], v[102:103], v[106:107]
	v_pk_mul_f32 v[102:103], v[100:101], v[104:105]
	v_add_co_u32_e32 v104, vcc, s65, v144
	v_cvt_pk_bf16_f32 v100, v108, v109
	v_cvt_pk_bf16_f32 v101, v110, v111
	v_cvt_pk_bf16_f32 v102, v102, v103
	v_cvt_pk_bf16_f32 v103, v106, v107
	v_addc_co_u32_e32 v105, vcc, 0, v145, vcc
	global_store_dwordx4 v[104:105], v[100:103], off sc1
	s_nop 1
	v_pk_mul_f32 v[100:101], v[94:95], s[74:75] op_sel_hi:[1,0]
	v_pk_mul_f32 v[102:103], v[96:97], s[74:75] op_sel_hi:[1,0]
	v_exp_f32_e32 v100, v100
	v_exp_f32_e32 v101, v101
	v_exp_f32_e32 v102, v102
	v_exp_f32_e32 v103, v103
	v_pk_add_f32 v[100:101], v[100:101], 1.0 op_sel_hi:[1,0]
	s_nop 0
	v_rcp_f32_e32 v100, v100
	v_pk_add_f32 v[102:103], v[102:103], 1.0 op_sel_hi:[1,0]
	v_rcp_f32_e32 v101, v101
	v_rcp_f32_e32 v102, v102
	v_rcp_f32_e32 v103, v103
	v_pk_mul_f32 v[94:95], v[94:95], v[100:101]
	s_nop 0
	v_pk_mul_f32 v[90:91], v[90:91], v[94:95]
	v_pk_mul_f32 v[96:97], v[96:97], v[102:103]
	v_pk_mul_f32 v[94:95], v[86:87], s[74:75] op_sel_hi:[1,0]
	v_pk_mul_f32 v[92:93], v[92:93], v[96:97]
	v_pk_mul_f32 v[96:97], v[88:89], s[74:75] op_sel_hi:[1,0]
	v_exp_f32_e32 v94, v94
	v_exp_f32_e32 v95, v95
	v_exp_f32_e32 v96, v96
	v_exp_f32_e32 v97, v97
	v_pk_add_f32 v[94:95], v[94:95], 1.0 op_sel_hi:[1,0]
	s_nop 0
	v_rcp_f32_e32 v94, v94
	v_pk_add_f32 v[96:97], v[96:97], 1.0 op_sel_hi:[1,0]
	v_rcp_f32_e32 v95, v95
	v_rcp_f32_e32 v96, v96
	v_rcp_f32_e32 v97, v97
	v_pk_mul_f32 v[86:87], v[86:87], v[94:95]
	v_pk_mul_f32 v[88:89], v[88:89], v[96:97]
	s_nop 0
	v_pk_mul_f32 v[88:89], v[84:85], v[88:89]
	v_pk_mul_f32 v[84:85], v[82:83], v[86:87]
	v_add_co_u32_e32 v86, vcc, s64, v144
	v_cvt_pk_bf16_f32 v82, v90, v91
	v_cvt_pk_bf16_f32 v83, v92, v93
	v_cvt_pk_bf16_f32 v84, v84, v85
	v_cvt_pk_bf16_f32 v85, v88, v89
	v_addc_co_u32_e32 v87, vcc, 0, v145, vcc
	global_store_dwordx4 v[86:87], v[82:85], off sc1
	s_nop 1
	v_pk_mul_f32 v[82:83], v[78:79], s[74:75] op_sel_hi:[1,0]
	v_pk_mul_f32 v[84:85], v[80:81], s[74:75] op_sel_hi:[1,0]
	v_exp_f32_e32 v82, v82
	v_exp_f32_e32 v83, v83
	v_exp_f32_e32 v84, v84
	v_exp_f32_e32 v85, v85
	v_pk_add_f32 v[82:83], v[82:83], 1.0 op_sel_hi:[1,0]
	s_nop 0
	v_rcp_f32_e32 v82, v82
	v_pk_add_f32 v[84:85], v[84:85], 1.0 op_sel_hi:[1,0]
	v_rcp_f32_e32 v83, v83
	v_rcp_f32_e32 v84, v84
	v_rcp_f32_e32 v85, v85
	v_pk_mul_f32 v[78:79], v[78:79], v[82:83]
	s_nop 0
	v_pk_mul_f32 v[74:75], v[74:75], v[78:79]
	v_pk_mul_f32 v[80:81], v[80:81], v[84:85]
	v_pk_mul_f32 v[78:79], v[70:71], s[74:75] op_sel_hi:[1,0]
	v_pk_mul_f32 v[76:77], v[76:77], v[80:81]
; __device__ __forceinline__ u32x4 pack8(f32x4 v0, f32x4 v1) { u32x4 w; w.x = cvt_pk_bf16(v0[0], v0[1]); w.y = cvt_pk_bf16(v0[2], v0[3]); w.z = cvt_pk_bf16(v1[0], v1[1]); w.w = cvt_pk_bf16(v1[2], v1[3]); return w; }
;     __device__ __forceinline__ void operator()(const f32x4 (&acc)[2][2][4][2], const Unit& u, int wr, int wc, int fr, int fq) const {
;         const int row0 = u.pm * BM + wr * 64 + fr, col0 = u.pn * HALF + wc * 32 + 8 * fq;
;         bf16_t* const p0 = ACT + (size_t)row0 * 5632 + col0;
; #pragma unroll
;         for (int ai = 0; ai < 2; ++ai)
; #pragma unroll
;             for (int m = 0; m < 4; ++m) {
;                 const f32x4 g0 = acc[ai][0][m][0], g1 = acc[ai][0][m][1];
;                 const f32x4 v0 = g0 * sigmoid4(g0) * acc[ai][1][m][0], v1 = g1 * sigmoid4(g1) * acc[ai][1][m][1];
;                 store16_wt(p0 + (size_t)(ai * HALF + m * 16) * 5632, pack8(v0, v1)); }
;     }
	v_pk_mul_f32 v[80:81], v[72:73], s[74:75] op_sel_hi:[1,0]
	v_exp_f32_e32 v78, v78
	v_exp_f32_e32 v79, v79
	v_exp_f32_e32 v80, v80
	v_exp_f32_e32 v81, v81
	v_pk_add_f32 v[78:79], v[78:79], 1.0 op_sel_hi:[1,0]
	s_nop 0
	v_rcp_f32_e32 v78, v78
	v_pk_add_f32 v[80:81], v[80:81], 1.0 op_sel_hi:[1,0]
	v_rcp_f32_e32 v79, v79
	v_rcp_f32_e32 v80, v80
	v_rcp_f32_e32 v81, v81
	v_pk_mul_f32 v[70:71], v[70:71], v[78:79]
	v_pk_mul_f32 v[72:73], v[72:73], v[80:81]
	s_nop 0
	v_pk_mul_f32 v[72:73], v[68:69], v[72:73]
	v_pk_mul_f32 v[68:69], v[66:67], v[70:71]
	v_add_co_u32_e32 v70, vcc, s66, v144
	v_cvt_pk_bf16_f32 v66, v74, v75
	v_cvt_pk_bf16_f32 v67, v76, v77
	v_cvt_pk_bf16_f32 v68, v68, v69
	v_cvt_pk_bf16_f32 v69, v72, v73
	v_addc_co_u32_e32 v71, vcc, 0, v145, vcc
	global_store_dwordx4 v[70:71], v[66:69], off sc1
	s_nop 1
	v_pk_mul_f32 v[66:67], v[62:63], s[74:75] op_sel_hi:[1,0]
	v_pk_mul_f32 v[68:69], v[64:65], s[74:75] op_sel_hi:[1,0]
	v_exp_f32_e32 v66, v66
	v_exp_f32_e32 v67, v67
	v_exp_f32_e32 v68, v68
	v_exp_f32_e32 v69, v69
	v_pk_add_f32 v[66:67], v[66:67], 1.0 op_sel_hi:[1,0]
	s_nop 0
	v_rcp_f32_e32 v66, v66
	v_pk_add_f32 v[68:69], v[68:69], 1.0 op_sel_hi:[1,0]
	v_rcp_f32_e32 v67, v67
	v_rcp_f32_e32 v68, v68
	v_rcp_f32_e32 v69, v69
	v_pk_mul_f32 v[62:63], v[62:63], v[66:67]
	s_nop 0
	v_pk_mul_f32 v[58:59], v[58:59], v[62:63]
	v_pk_mul_f32 v[64:65], v[64:65], v[68:69]
	v_pk_mul_f32 v[62:63], v[54:55], s[74:75] op_sel_hi:[1,0]
	v_pk_mul_f32 v[60:61], v[60:61], v[64:65]
	v_pk_mul_f32 v[64:65], v[56:57], s[74:75] op_sel_hi:[1,0]
	v_exp_f32_e32 v62, v62
	v_exp_f32_e32 v63, v63
	v_exp_f32_e32 v64, v64
	v_exp_f32_e32 v65, v65
	v_pk_add_f32 v[62:63], v[62:63], 1.0 op_sel_hi:[1,0]
	s_nop 0
	v_rcp_f32_e32 v62, v62
	v_pk_add_f32 v[64:65], v[64:65], 1.0 op_sel_hi:[1,0]
	v_rcp_f32_e32 v63, v63
	v_rcp_f32_e32 v64, v64
	v_rcp_f32_e32 v65, v65
	v_pk_mul_f32 v[54:55], v[54:55], v[62:63]
	v_pk_mul_f32 v[56:57], v[56:57], v[64:65]
	s_nop 0
	v_pk_mul_f32 v[56:57], v[52:53], v[56:57]
	v_pk_mul_f32 v[52:53], v[50:51], v[54:55]
	v_add_co_u32_e32 v54, vcc, s0, v144
	v_cvt_pk_bf16_f32 v50, v58, v59
	v_cvt_pk_bf16_f32 v51, v60, v61
	v_cvt_pk_bf16_f32 v52, v52, v53
	v_cvt_pk_bf16_f32 v53, v56, v57
	v_addc_co_u32_e32 v55, vcc, 0, v145, vcc
	global_store_dwordx4 v[54:55], v[50:53], off sc1
	s_mov_b32 s0, 0x18c000
	s_nop 0
	v_pk_mul_f32 v[50:51], v[46:47], s[74:75] op_sel_hi:[1,0]
	v_pk_mul_f32 v[52:53], v[48:49], s[74:75] op_sel_hi:[1,0]
	v_exp_f32_e32 v50, v50
	v_exp_f32_e32 v51, v51
	v_exp_f32_e32 v52, v52
	v_exp_f32_e32 v53, v53
	v_pk_add_f32 v[50:51], v[50:51], 1.0 op_sel_hi:[1,0]
	s_nop 0
	v_rcp_f32_e32 v50, v50
	v_pk_add_f32 v[52:53], v[52:53], 1.0 op_sel_hi:[1,0]
	v_rcp_f32_e32 v51, v51
	v_rcp_f32_e32 v52, v52
	v_rcp_f32_e32 v53, v53
	v_pk_mul_f32 v[46:47], v[46:47], v[50:51]
	s_nop 0
	v_pk_mul_f32 v[42:43], v[42:43], v[46:47]
	v_pk_mul_f32 v[48:49], v[48:49], v[52:53]
	v_pk_mul_f32 v[46:47], v[38:39], s[74:75] op_sel_hi:[1,0]
	v_pk_mul_f32 v[44:45], v[44:45], v[48:49]
	v_pk_mul_f32 v[48:49], v[40:41], s[74:75] op_sel_hi:[1,0]
	v_exp_f32_e32 v46, v46
	v_exp_f32_e32 v47, v47
	v_exp_f32_e32 v48, v48
	v_exp_f32_e32 v49, v49
	v_pk_add_f32 v[46:47], v[46:47], 1.0 op_sel_hi:[1,0]
	s_nop 0
	v_rcp_f32_e32 v46, v46
	v_pk_add_f32 v[48:49], v[48:49], 1.0 op_sel_hi:[1,0]
	v_rcp_f32_e32 v47, v47
	v_rcp_f32_e32 v48, v48
	v_rcp_f32_e32 v49, v49
	v_pk_mul_f32 v[38:39], v[38:39], v[46:47]
	v_pk_mul_f32 v[40:41], v[40:41], v[48:49]
	s_nop 0
	v_pk_mul_f32 v[40:41], v[36:37], v[40:41]
	v_pk_mul_f32 v[36:37], v[34:35], v[38:39]
	v_add_co_u32_e32 v38, vcc, s0, v144
	v_cvt_pk_bf16_f32 v34, v42, v43
	v_cvt_pk_bf16_f32 v35, v44, v45
	v_cvt_pk_bf16_f32 v36, v36, v37
	v_cvt_pk_bf16_f32 v37, v40, v41
	v_addc_co_u32_e32 v39, vcc, 0, v145, vcc
	global_store_dwordx4 v[38:39], v[34:37], off sc1
	s_mov_b32 s0, 0x1b8000
	s_nop 0
	v_pk_mul_f32 v[34:35], v[30:31], s[74:75] op_sel_hi:[1,0]
	v_pk_mul_f32 v[36:37], v[32:33], s[74:75] op_sel_hi:[1,0]
	v_exp_f32_e32 v34, v34
	v_exp_f32_e32 v35, v35
	v_exp_f32_e32 v36, v36
	v_exp_f32_e32 v37, v37
	v_pk_add_f32 v[34:35], v[34:35], 1.0 op_sel_hi:[1,0]
	s_nop 0
	v_rcp_f32_e32 v34, v34
	v_pk_add_f32 v[36:37], v[36:37], 1.0 op_sel_hi:[1,0]
	v_rcp_f32_e32 v35, v35
	v_rcp_f32_e32 v36, v36
	v_rcp_f32_e32 v37, v37
	v_pk_mul_f32 v[30:31], v[30:31], v[34:35]
	s_nop 0
	v_pk_mul_f32 v[26:27], v[26:27], v[30:31]
	v_pk_mul_f32 v[32:33], v[32:33], v[36:37]
	v_pk_mul_f32 v[30:31], v[22:23], s[74:75] op_sel_hi:[1,0]
	v_pk_mul_f32 v[28:29], v[28:29], v[32:33]
	v_pk_mul_f32 v[32:33], v[24:25], s[74:75] op_sel_hi:[1,0]
	v_exp_f32_e32 v30, v30
	v_exp_f32_e32 v31, v31
	v_exp_f32_e32 v32, v32
	v_exp_f32_e32 v33, v33
	v_pk_add_f32 v[30:31], v[30:31], 1.0 op_sel_hi:[1,0]
	s_nop 0
	v_rcp_f32_e32 v30, v30
	v_pk_add_f32 v[32:33], v[32:33], 1.0 op_sel_hi:[1,0]
	v_rcp_f32_e32 v31, v31
	v_rcp_f32_e32 v32, v32
	v_rcp_f32_e32 v33, v33
	v_pk_mul_f32 v[22:23], v[22:23], v[30:31]
	v_pk_mul_f32 v[24:25], v[24:25], v[32:33]
	s_nop 0
	v_pk_mul_f32 v[24:25], v[20:21], v[24:25]
	v_pk_mul_f32 v[20:21], v[18:19], v[22:23]
	v_add_co_u32_e32 v22, vcc, s0, v144
	v_cvt_pk_bf16_f32 v18, v26, v27
	v_cvt_pk_bf16_f32 v19, v28, v29
	v_cvt_pk_bf16_f32 v20, v20, v21
	v_cvt_pk_bf16_f32 v21, v24, v25
	v_addc_co_u32_e32 v23, vcc, 0, v145, vcc
	global_store_dwordx4 v[22:23], v[18:21], off sc1
	s_nop 1
	v_pk_mul_f32 v[18:19], v[14:15], s[74:75] op_sel_hi:[1,0]
	v_pk_mul_f32 v[20:21], v[16:17], s[74:75] op_sel_hi:[1,0]
	v_exp_f32_e32 v18, v18
	v_exp_f32_e32 v19, v19
	v_exp_f32_e32 v20, v20
	v_exp_f32_e32 v21, v21
	v_pk_add_f32 v[18:19], v[18:19], 1.0 op_sel_hi:[1,0]
	s_nop 0
	v_rcp_f32_e32 v18, v18
	v_pk_add_f32 v[20:21], v[20:21], 1.0 op_sel_hi:[1,0]
	v_rcp_f32_e32 v19, v19
	v_rcp_f32_e32 v20, v20
	v_rcp_f32_e32 v21, v21
	v_pk_mul_f32 v[14:15], v[14:15], v[18:19]
	s_nop 0
	v_pk_mul_f32 v[10:11], v[10:11], v[14:15]
	v_pk_mul_f32 v[16:17], v[16:17], v[20:21]
	v_pk_mul_f32 v[14:15], v[6:7], s[74:75] op_sel_hi:[1,0]
	v_pk_mul_f32 v[12:13], v[12:13], v[16:17]
	v_pk_mul_f32 v[16:17], v[8:9], s[74:75] op_sel_hi:[1,0]
	v_exp_f32_e32 v14, v14
	v_exp_f32_e32 v15, v15
	v_exp_f32_e32 v16, v16
	v_exp_f32_e32 v17, v17
	v_pk_add_f32 v[14:15], v[14:15], 1.0 op_sel_hi:[1,0]
	s_nop 0
	v_rcp_f32_e32 v14, v14
	v_pk_add_f32 v[16:17], v[16:17], 1.0 op_sel_hi:[1,0]
	v_rcp_f32_e32 v15, v15
	v_rcp_f32_e32 v16, v16
	v_rcp_f32_e32 v17, v17
	v_pk_mul_f32 v[6:7], v[6:7], v[14:15]
	v_pk_mul_f32 v[8:9], v[8:9], v[16:17]
	s_nop 0
	v_pk_mul_f32 v[8:9], v[4:5], v[8:9]
	v_pk_mul_f32 v[4:5], v[2:3], v[6:7]
	v_add_co_u32_e32 v6, vcc, 0x1e4000, v144
	v_cvt_pk_bf16_f32 v2, v10, v11
	s_nop 0
	v_addc_co_u32_e32 v7, vcc, 0, v145, vcc
	v_cvt_pk_bf16_f32 v3, v12, v13
	v_cvt_pk_bf16_f32 v4, v4, v5
	v_cvt_pk_bf16_f32 v5, v8, v9
	s_andn2_b64 vcc, exec, s[38:39]
	global_store_dwordx4 v[6:7], v[2:5], off sc1
	s_cbranch_vccnz .LBB0_1454
	s_andn2_b64 vcc, exec, s[6:7]
	s_cbranch_vccnz .LBB0_1453
	s_barrier
	s_branch .LBB0_1453
